# in-projection epilogue: the 8 row-group norm-statistic loads issued together at epilogue start; LRU-B and ctx-differential unit waits: L1 invalidate issued before the first counter poll instead of aft
# baseline (speedup 1.0000x reference)
.LBB0_487:
	s_lshl_b32 s13, s12, 8
	v_add_u32_e32 v170, s60, v162
	v_add_u32_e32 v168, s13, v170
	v_ashrrev_i32_e32 v169, 31, v168
	v_lshlrev_b32_e32 v166, 2, v64
	v_lshlrev_b64 v[162:163], 6, v[168:169]
	v_ashrrev_i32_e32 v167, 31, v166
	v_lshl_add_u64 v[162:163], s[14:15], 0, v[162:163]
	v_lshl_add_u64 v[162:163], v[166:167], 2, v[162:163]
	flat_load_dwordx4 v[162:165], v[162:163]
	v_add_u32_e32 v200, 16, v168
	v_ashrrev_i32_e32 v201, 31, v200
	v_lshlrev_b64 v[200:201], 6, v[200:201]
	v_lshl_add_u64 v[200:201], s[14:15], 0, v[200:201]
	v_lshl_add_u64 v[200:201], v[166:167], 2, v[200:201]
	global_load_dwordx4 v[200:203], v[200:201], off
	v_add_u32_e32 v204, 32, v168
	v_ashrrev_i32_e32 v205, 31, v204
	v_lshlrev_b64 v[204:205], 6, v[204:205]
	v_lshl_add_u64 v[204:205], s[14:15], 0, v[204:205]
	v_lshl_add_u64 v[204:205], v[166:167], 2, v[204:205]
	global_load_dwordx4 v[204:207], v[204:205], off
	v_add_u32_e32 v216, 48, v168
	v_ashrrev_i32_e32 v217, 31, v216
	v_lshlrev_b64 v[216:217], 6, v[216:217]
	v_lshl_add_u64 v[216:217], s[14:15], 0, v[216:217]
	v_lshl_add_u64 v[216:217], v[166:167], 2, v[216:217]
	global_load_dwordx4 v[216:219], v[216:217], off
	v_add_u32_e32 v220, 0x80, v168
	v_ashrrev_i32_e32 v221, 31, v220
	v_lshlrev_b64 v[220:221], 6, v[220:221]
	v_lshl_add_u64 v[220:221], s[14:15], 0, v[220:221]
	v_lshl_add_u64 v[220:221], v[166:167], 2, v[220:221]
	global_load_dwordx4 v[220:223], v[220:221], off
	v_add_u32_e32 v224, 0x90, v168
	v_ashrrev_i32_e32 v225, 31, v224
	v_lshlrev_b64 v[224:225], 6, v[224:225]
	v_lshl_add_u64 v[224:225], s[14:15], 0, v[224:225]
	v_lshl_add_u64 v[224:225], v[166:167], 2, v[224:225]
	global_load_dwordx4 v[224:227], v[224:225], off
	v_add_u32_e32 v240, 0xa0, v168
	v_ashrrev_i32_e32 v241, 31, v240
	v_lshlrev_b64 v[240:241], 6, v[240:241]
	v_lshl_add_u64 v[240:241], s[14:15], 0, v[240:241]
	v_lshl_add_u64 v[240:241], v[166:167], 2, v[240:241]
	global_load_dwordx4 v[240:243], v[240:241], off
	v_add_u32_e32 v244, 0xb0, v168
	v_ashrrev_i32_e32 v245, 31, v244
	v_lshlrev_b64 v[244:245], 6, v[244:245]
	v_lshl_add_u64 v[244:245], s[14:15], 0, v[244:245]
	v_lshl_add_u64 v[244:245], v[166:167], 2, v[244:245]
	global_load_dwordx4 v[244:247], v[244:245], off
	v_and_b32_e32 v169, 0x3ff, v168
	s_cmp_gt_i32 s23, 63
	s_waitcnt vmcnt(0) lgkmcnt(0)
	v_add_f32_e32 v64, v162, v163
	v_add_f32_e32 v162, v164, v165
	v_add_f32_e32 v64, v64, v162
	v_mov_b32_e32 v162, v64
	s_nop 1
	v_permlane16_swap_b32_e32 v64, v162
	v_add_f32_e32 v64, v64, v162
	v_mov_b32_e32 v162, v64
	s_nop 1
	v_permlane32_swap_b32_e32 v64, v162
	v_add_f32_e32 v64, v64, v162
	v_and_b32_e32 v163, 56, v158
	v_fmamk_f32 v171, v64, 0x3a800000, v229
	v_lshlrev_b32_e32 v64, 6, v169
	v_cmp_gt_f32_e32 vcc, s55, v171
	v_lshlrev_b32_e32 v64, 2, v64
	v_lshlrev_b32_e32 v162, 2, v163
	s_cbranch_scc0 .LBB0_489
	v_lshl_add_u64 v[164:165], s[16:17], 0, v[64:65]
	v_mov_b32_e32 v163, v65
	v_lshl_add_u64 v[164:165], v[164:165], 0, v[162:163]
	s_mov_b64 s[56:57], 0
	s_mov_b64 s[6:7], -1
	s_branch .LBB0_490

.LBB0_523:
	s_nop 1
	v_add_u32_e32 v130, 16, v168
	v_ashrrev_i32_e32 v131, 31, v130
	s_cmp_gt_i32 s23, 63
	v_add_f32_e32 v64, v200, v201
	v_add_f32_e32 v131, v202, v203
	v_add_f32_e32 v64, v64, v131
	v_mov_b32_e32 v131, v64
	s_nop 1
	v_permlane16_swap_b32_e32 v64, v131
	v_add_f32_e32 v64, v64, v131
	v_mov_b32_e32 v131, v64
	s_nop 1
	v_permlane32_swap_b32_e32 v64, v131
	v_add_f32_e32 v64, v64, v131
	v_and_b32_e32 v131, 0x3ff, v130
	v_fmamk_f32 v132, v64, 0x3a800000, v229
	v_lshlrev_b32_e32 v64, 6, v131
	v_cmp_gt_f32_e32 vcc, s55, v132
	v_lshlrev_b32_e32 v64, 2, v64
	s_cbranch_scc0 .LBB0_529
	v_lshl_add_u64 v[134:135], s[16:17], 0, v[64:65]
	v_mov_b32_e32 v163, v65
	v_lshl_add_u64 v[134:135], v[134:135], 0, v[162:163]
	s_mov_b64 s[56:57], 0
	s_mov_b64 s[34:35], -1
	s_branch .LBB0_530

.LBB0_563:
	s_nop 1
	v_add_u32_e32 v114, 32, v168
	v_ashrrev_i32_e32 v115, 31, v114
	s_cmp_gt_i32 s23, 63
	v_add_f32_e32 v64, v204, v205
	v_add_f32_e32 v115, v206, v207
	v_add_f32_e32 v64, v64, v115
	v_mov_b32_e32 v115, v64
	s_nop 1
	v_permlane16_swap_b32_e32 v64, v115
	v_add_f32_e32 v64, v64, v115
	v_mov_b32_e32 v115, v64
	s_nop 1
	v_permlane32_swap_b32_e32 v64, v115
	v_add_f32_e32 v64, v64, v115
	v_and_b32_e32 v115, 0x3ff, v114
	v_fmamk_f32 v116, v64, 0x3a800000, v229
	v_lshlrev_b32_e32 v64, 6, v115
	v_cmp_gt_f32_e32 vcc, s55, v116
	v_lshlrev_b32_e32 v64, 2, v64
	s_cbranch_scc0 .LBB0_569
	v_lshl_add_u64 v[118:119], s[16:17], 0, v[64:65]
	v_mov_b32_e32 v163, v65
	v_lshl_add_u64 v[118:119], v[118:119], 0, v[162:163]
	s_mov_b64 s[56:57], 0
	s_mov_b64 s[34:35], -1
	s_branch .LBB0_570

.LBB0_603:
	s_nop 1
	v_add_u32_e32 v98, 48, v168
	v_ashrrev_i32_e32 v99, 31, v98
	s_cmp_gt_i32 s23, 63
	v_add_f32_e32 v64, v216, v217
	v_add_f32_e32 v99, v218, v219
	v_add_f32_e32 v64, v64, v99
	v_mov_b32_e32 v99, v64
	s_nop 1
	v_permlane16_swap_b32_e32 v64, v99
	v_add_f32_e32 v64, v64, v99
	v_mov_b32_e32 v99, v64
	s_nop 1
	v_permlane32_swap_b32_e32 v64, v99
	v_add_f32_e32 v64, v64, v99
	v_and_b32_e32 v99, 0x3ff, v98
	v_fmamk_f32 v100, v64, 0x3a800000, v229
	v_lshlrev_b32_e32 v64, 6, v99
	v_cmp_gt_f32_e32 vcc, s55, v100
	v_lshlrev_b32_e32 v64, 2, v64
	s_cbranch_scc0 .LBB0_609
	v_lshl_add_u64 v[102:103], s[16:17], 0, v[64:65]
	v_mov_b32_e32 v163, v65
	v_lshl_add_u64 v[102:103], v[102:103], 0, v[162:163]
	s_mov_b64 s[56:57], 0
	s_mov_b64 s[34:35], -1
	s_branch .LBB0_610

.LBB0_643:
	s_nop 1
	v_add_u32_e32 v82, 0x80, v168
	v_ashrrev_i32_e32 v83, 31, v82
	s_cmp_gt_i32 s23, 63
	v_add_f32_e32 v64, v220, v221
	v_add_f32_e32 v83, v222, v223
	v_add_f32_e32 v64, v64, v83
	v_mov_b32_e32 v83, v64
	s_nop 1
	v_permlane16_swap_b32_e32 v64, v83
	v_add_f32_e32 v64, v64, v83
	v_mov_b32_e32 v83, v64
	s_nop 1
	v_permlane32_swap_b32_e32 v64, v83
	v_add_f32_e32 v64, v64, v83
	v_and_b32_e32 v83, 0x3ff, v82
	v_fmamk_f32 v84, v64, 0x3a800000, v229
	v_lshlrev_b32_e32 v64, 6, v83
	v_cmp_gt_f32_e32 vcc, s55, v84
	v_lshlrev_b32_e32 v64, 2, v64
	s_cbranch_scc0 .LBB0_649
	v_lshl_add_u64 v[86:87], s[16:17], 0, v[64:65]
	v_mov_b32_e32 v163, v65
	v_lshl_add_u64 v[86:87], v[86:87], 0, v[162:163]
	s_mov_b64 s[56:57], 0
	s_mov_b64 s[34:35], -1
	s_branch .LBB0_650

.LBB0_683:
	s_nop 1
	v_add_u32_e32 v66, 0x90, v168
	v_ashrrev_i32_e32 v67, 31, v66
	s_cmp_gt_i32 s23, 63
	v_add_f32_e32 v64, v224, v225
	v_add_f32_e32 v67, v226, v227
	v_add_f32_e32 v64, v64, v67
	v_mov_b32_e32 v67, v64
	s_nop 1
	v_permlane16_swap_b32_e32 v64, v67
	v_add_f32_e32 v64, v64, v67
	v_mov_b32_e32 v67, v64
	s_nop 1
	v_permlane32_swap_b32_e32 v64, v67
	v_add_f32_e32 v64, v64, v67
	v_and_b32_e32 v67, 0x3ff, v66
	v_fmamk_f32 v68, v64, 0x3a800000, v229
	v_lshlrev_b32_e32 v64, 6, v67
	v_cmp_gt_f32_e32 vcc, s55, v68
	v_lshlrev_b32_e32 v64, 2, v64
	s_cbranch_scc0 .LBB0_689
	v_lshl_add_u64 v[70:71], s[16:17], 0, v[64:65]
	v_mov_b32_e32 v163, v65
	v_lshl_add_u64 v[70:71], v[70:71], 0, v[162:163]
	s_mov_b64 s[56:57], 0
	s_mov_b64 s[34:35], -1
	s_branch .LBB0_690

.LBB0_723:
	s_nop 1
	v_add_u32_e32 v48, 0xa0, v168
	v_ashrrev_i32_e32 v49, 31, v48
	s_cmp_gt_i32 s23, 63
	v_add_f32_e32 v49, v240, v241
	v_add_f32_e32 v50, v242, v243
	v_add_f32_e32 v49, v49, v50
	v_mov_b32_e32 v50, v49
	s_nop 1
	v_permlane16_swap_b32_e32 v49, v50
	v_add_f32_e32 v49, v49, v50
	v_mov_b32_e32 v50, v49
	s_nop 1
	v_permlane32_swap_b32_e32 v49, v50
	v_add_f32_e32 v49, v49, v50
	v_fmamk_f32 v50, v49, 0x3a800000, v229
	v_and_b32_e32 v49, 0x3ff, v48
	v_lshlrev_b32_e32 v51, 6, v49
	v_cmp_gt_f32_e32 vcc, s55, v50
	v_lshlrev_b32_e32 v64, 2, v51
	s_cbranch_scc0 .LBB0_729
	v_lshl_add_u64 v[52:53], s[16:17], 0, v[64:65]
	v_mov_b32_e32 v163, v65
	v_lshl_add_u64 v[52:53], v[52:53], 0, v[162:163]
	s_mov_b64 s[56:57], 0
	s_mov_b64 s[34:35], -1
	s_branch .LBB0_730

.LBB0_763:
	s_nop 1
	v_add_u32_e32 v16, 0xb0, v168
	v_ashrrev_i32_e32 v17, 31, v16
	s_cmp_gt_i32 s23, 63
	v_add_f32_e32 v17, v244, v245
	v_add_f32_e32 v18, v246, v247
	v_add_f32_e32 v17, v17, v18
	v_mov_b32_e32 v18, v17
	s_nop 1
	v_permlane16_swap_b32_e32 v17, v18
	v_add_f32_e32 v17, v17, v18
	v_mov_b32_e32 v18, v17
	s_nop 1
	v_permlane32_swap_b32_e32 v17, v18
	v_add_f32_e32 v17, v17, v18
	v_fmamk_f32 v18, v17, 0x3a800000, v229
	v_and_b32_e32 v17, 0x3ff, v16
	v_lshlrev_b32_e32 v19, 6, v17
	v_cmp_gt_f32_e32 vcc, s55, v18
	v_lshlrev_b32_e32 v64, 2, v19
	s_cbranch_scc0 .LBB0_769
	v_lshl_add_u64 v[20:21], s[16:17], 0, v[64:65]
	v_mov_b32_e32 v163, v65
	v_lshl_add_u64 v[20:21], v[20:21], 0, v[162:163]
	s_mov_b64 s[56:57], 0
	s_mov_b64 s[34:35], -1
	s_branch .LBB0_770

.LBB0_960:
	s_or_b64 exec, exec, s[0:1]
	s_mov_b64 s[0:1], s[80:81]
	s_mov_b32 s45, s74
	s_cmp_gt_i32 s86, 15
	s_mov_b64 s[6:7], -1
	s_cbranch_scc0 .LBB0_1822
	s_cmpk_gt_u32 s86, 0x10f
	s_cbranch_scc0 .LBB0_1541
	s_cmpk_gt_u32 s86, 0x18f
	s_cbranch_scc0 .LBB0_1260
	s_cmpk_gt_u32 s86, 0x28f
	s_cbranch_scc0 .LBB0_1199
	s_cmpk_gt_u32 s86, 0x38f
	s_cbranch_scc0 .LBB0_1145
	s_cmpk_gt_u32 s86, 0x48f
	s_cbranch_scc0 .LBB0_1078
	s_cmpk_gt_u32 s86, 0x50f
	s_cbranch_scc0 .LBB0_1053
	s_cmpk_gt_u32 s86, 0x58f
	s_cbranch_scc0 .LBB0_1046
	s_cmpk_gt_u32 s86, 0x5cf
	s_cbranch_scc0 .LBB0_1036
	s_cmpk_gt_u32 s86, 0x6cf
	s_cbranch_scc0 .LBB0_1018
	s_cmpk_gt_u32 s86, 0x74f
	s_cbranch_scc0 .LBB0_1004
	s_and_saveexec_b64 s[6:7], s[26:27]
	s_cbranch_execz .LBB0_984
	buffer_inv sc1
	global_load_dword v0, v65, s[70:71] offset:2304 sc1
	s_waitcnt vmcnt(0)
	v_cmp_lt_u32_e32 vcc, 15, v0
	s_cbranch_vccnz .LBB0_983
	s_mov_b32 s10, 0x3ffff8
	s_branch .LBB0_975

.LBB0_975:
	s_sleep 2
	global_load_dword v0, v65, s[70:71] offset:2304 sc1
	s_mov_b64 s[8:9], -1
	s_waitcnt vmcnt(0)
	v_cmp_lt_u32_e32 vcc, 15, v0
	s_cbranch_vccnz .LBB0_974
	s_sleep 2
	global_load_dword v0, v65, s[70:71] offset:2304 sc1
	s_waitcnt vmcnt(0)
	v_cmp_gt_u32_e32 vcc, 16, v0
	s_cbranch_vccz .LBB0_974
	s_sleep 2
	global_load_dword v0, v65, s[70:71] offset:2304 sc1
	s_waitcnt vmcnt(0)
	v_cmp_gt_u32_e32 vcc, 16, v0
	s_cbranch_vccz .LBB0_974
	s_sleep 2
	global_load_dword v0, v65, s[70:71] offset:2304 sc1
	s_waitcnt vmcnt(0)
	v_cmp_gt_u32_e32 vcc, 16, v0
	s_cbranch_vccz .LBB0_974
	s_sleep 2
	global_load_dword v0, v65, s[70:71] offset:2304 sc1
	s_waitcnt vmcnt(0)
	v_cmp_gt_u32_e32 vcc, 16, v0
	s_cbranch_vccz .LBB0_974
	s_sleep 2
	global_load_dword v0, v65, s[70:71] offset:2304 sc1
	s_waitcnt vmcnt(0)
	v_cmp_gt_u32_e32 vcc, 16, v0
	s_cbranch_vccz .LBB0_974
	s_sleep 2
	global_load_dword v0, v65, s[70:71] offset:2304 sc1
	s_cmp_eq_u32 s10, 0
	s_cselect_b64 s[8:9], -1, 0
	s_waitcnt vmcnt(0)
	v_cmp_lt_u32_e32 vcc, 15, v0
	s_or_b64 s[8:9], vcc, s[8:9]
	s_andn2_b64 vcc, exec, s[8:9]
	s_mov_b64 s[8:9], -1
	s_cbranch_vccz .LBB0_974
	s_sleep 2
	global_load_dword v0, v65, s[70:71] offset:2304 sc1
	s_add_i32 s10, s10, -8
	s_waitcnt vmcnt(0)
	v_cmp_lt_u32_e64 s[8:9], 15, v0
	s_branch .LBB0_974
.LBB0_983:
	s_waitcnt vmcnt(0)
.LBB0_984:
	s_or_b64 exec, exec, s[6:7]
	v_mov_b32_e32 v11, v228
	s_barrier
	s_load_dwordx2 s[6:7], s[0:1], 0x100
	s_lshl_b32 s8, s86, 5
	s_and_b32 s14, s8, 0x7fffff00
	s_add_i32 s14, s14, 0xffff1600
	v_and_b32_e32 v10, 15, v11
	s_waitcnt lgkmcnt(0)
	s_add_u32 s10, s6, 0xae00000
	s_addc_u32 s11, s7, 0
	s_lshl_b32 s9, s86, 7
	s_and_b32 s9, s9, 0x80
	v_ashrrev_i32_e32 v0, 2, v11
	s_and_b32 s12, s8, 0xc0
	s_or_b32 s8, s9, s14
	v_and_b32_e32 v0, -16, v0
	v_or_b32_e32 v1, s8, v10
	v_add_u32_e32 v78, v1, v0
	v_mov_b64_e32 v[0:1], s[10:11]
	v_mad_i64_i32 v[0:1], s[8:9], v78, s93, v[0:1]
	s_lshl_b32 s8, s12, 1
	s_mov_b32 s9, s97
	v_lshl_add_u64 v[0:1], v[0:1], 0, s[8:9]
	v_and_b32_e32 v8, 48, v11
	v_mov_b32_e32 v9, v65
	v_lshl_add_u64 v[0:1], v[0:1], 0, v[8:9]
	s_mov_b64 s[12:13], 0x1000
	v_lshl_add_u64 v[4:5], v[0:1], 0, s[12:13]
	v_add_co_u32_e32 v0, vcc, 0x1000, v0
	v_and_b32_e32 v9, 63, v11
	s_nop 0
	v_addc_co_u32_e32 v1, vcc, 0, v1, vcc
	global_load_dwordx4 v[0:3], v[0:1], off
	s_nop 0
	global_load_dwordx4 v[4:7], v[4:5], off offset:64
	v_cmp_gt_u32_e32 vcc, 32, v9
	v_mov_b32_e32 v79, 0
	v_mov_b32_e32 v80, 0
	v_mov_b32_e32 v81, 0
	s_and_saveexec_b64 s[12:13], vcc
	s_cbranch_execz .LBB0_986
	s_load_dwordx2 s[16:17], s[0:1], 0xc0
	s_lshl_b32 s18, s45, 7
	s_ashr_i32 s19, s18, 31
	s_lshl_b64 s[18:19], s[18:19], 2
	v_lshlrev_b32_e32 v9, 2, v9
	s_waitcnt lgkmcnt(0)
	s_add_u32 s16, s16, s18
	s_addc_u32 s17, s17, s19
	global_load_dword v13, v9, s[16:17]
	global_load_dword v15, v9, s[16:17] offset:128
	global_load_dword v12, v9, s[16:17] offset:256
	global_load_dword v14, v9, s[16:17] offset:384
	s_waitcnt vmcnt(0)
	v_pk_mul_f32 v[80:81], v[12:13], v[14:15]

.LBB0_1019:
	v_mov_b32_e32 v50, v228
	s_load_dwordx2 s[8:9], s[0:1], 0x100
	s_add_i32 s6, s86, 0xfffffa30
	s_lshr_b32 s14, s6, 5
	s_bfe_u32 s15, s6, 0x20003
	s_lshl_b32 s16, s14, 2
	v_cmp_eq_u32_e32 vcc, 0, v50
	s_and_saveexec_b64 s[6:7], vcc
	s_cbranch_execz .LBB0_1032
	s_lshl_b32 s10, s45, 7
	s_ashr_i32 s11, s10, 31
	s_lshl_b64 s[10:11], s[10:11], 2
	s_waitcnt lgkmcnt(0)
	s_add_u32 s10, s8, s10
	s_addc_u32 s11, s9, s11
	s_lshl_b32 s12, s16, 2
	s_add_u32 s10, s10, s12
	s_addc_u32 s11, s11, 0
	s_lshl_b32 s12, s15, 2
	s_add_u32 s10, s10, s12
	s_addc_u32 s11, s11, 0
	s_add_u32 s10, s10, 0x1000
	s_addc_u32 s11, s11, 0
	buffer_inv sc1
	global_load_dword v0, v65, s[10:11] offset:256 sc1
	s_waitcnt vmcnt(0)
	v_cmp_lt_u32_e32 vcc, 7, v0
	s_cbranch_vccnz .LBB0_1031
	s_mov_b32 s17, 0x3ffff8
	s_branch .LBB0_1023

.LBB0_1023:
	s_sleep 2
	global_load_dword v0, v65, s[10:11] offset:256 sc1
	s_mov_b64 s[12:13], -1
	s_waitcnt vmcnt(0)
	v_cmp_lt_u32_e32 vcc, 7, v0
	s_cbranch_vccnz .LBB0_1022
	s_sleep 2
	global_load_dword v0, v65, s[10:11] offset:256 sc1
	s_waitcnt vmcnt(0)
	v_cmp_gt_u32_e32 vcc, 8, v0
	s_cbranch_vccz .LBB0_1022
	s_sleep 2
	global_load_dword v0, v65, s[10:11] offset:256 sc1
	s_waitcnt vmcnt(0)
	v_cmp_gt_u32_e32 vcc, 8, v0
	s_cbranch_vccz .LBB0_1022
	s_sleep 2
	global_load_dword v0, v65, s[10:11] offset:256 sc1
	s_waitcnt vmcnt(0)
	v_cmp_gt_u32_e32 vcc, 8, v0
	s_cbranch_vccz .LBB0_1022
	s_sleep 2
	global_load_dword v0, v65, s[10:11] offset:256 sc1
	s_waitcnt vmcnt(0)
	v_cmp_gt_u32_e32 vcc, 8, v0
	s_cbranch_vccz .LBB0_1022
	s_sleep 2
	global_load_dword v0, v65, s[10:11] offset:256 sc1
	s_waitcnt vmcnt(0)
	v_cmp_gt_u32_e32 vcc, 8, v0
	s_cbranch_vccz .LBB0_1022
	s_sleep 2
	global_load_dword v0, v65, s[10:11] offset:256 sc1
	s_cmp_eq_u32 s17, 0
	s_cselect_b64 s[12:13], -1, 0
	s_waitcnt vmcnt(0)
	v_cmp_lt_u32_e32 vcc, 7, v0
	s_or_b64 s[12:13], vcc, s[12:13]
	s_andn2_b64 vcc, exec, s[12:13]
	s_mov_b64 s[12:13], -1
	s_cbranch_vccz .LBB0_1022
	s_sleep 2
	global_load_dword v0, v65, s[10:11] offset:256 sc1
	s_add_i32 s17, s17, -8
	s_waitcnt vmcnt(0)
	v_cmp_lt_u32_e64 s[12:13], 7, v0
	s_branch .LBB0_1022
.LBB0_1031:
	s_waitcnt vmcnt(0)
.LBB0_1032:
	s_or_b64 exec, exec, s[6:7]
	s_and_b32 s13, s86, 7
	s_lshl_b32 s6, s14, 10
	s_lshl_b32 s7, s13, 7
	s_or_b32 s6, s6, s7
	v_lshlrev_b32_e32 v0, 2, v50
	s_add_i32 s10, s6, 0x1000
	s_lshl_b32 s12, s15, 6
	s_lshl_b32 s6, s15, 8
	v_and_b32_e32 v48, 60, v0
	s_waitcnt lgkmcnt(0)
	s_add_u32 s6, s8, s6
	v_lshlrev_b32_e32 v64, 2, v48
	s_addc_u32 s7, s9, 0
	v_lshl_add_u64 v[0:1], s[6:7], 0, v[64:65]
	s_mov_b64 s[6:7], 0x10800000
	v_lshl_add_u64 v[2:3], v[0:1], 0, s[6:7]
	s_mov_b64 s[6:7], 0x11800000
	v_lshl_add_u64 v[4:5], v[0:1], 0, s[6:7]
	s_mov_b64 s[6:7], 0x12800000
	v_lshl_add_u64 v[8:9], v[0:1], 0, s[6:7]
	v_ashrrev_i32_e32 v0, 4, v50
	v_add_u32_e32 v70, s10, v0
	v_ashrrev_i32_e32 v71, 31, v70
	v_lshlrev_b64 v[0:1], 10, v[70:71]
	v_lshl_add_u64 v[6:7], v[2:3], 0, v[0:1]
	v_lshl_add_u64 v[10:11], v[4:5], 0, v[0:1]
	s_barrier
	global_load_dwordx4 v[36:39], v[6:7], off
	global_load_dwordx4 v[40:43], v[10:11], off
	v_mov_b64_e32 v[10:11], s[8:9]
	v_mad_i64_i32 v[6:7], s[6:7], v70, s93, v[10:11]
	s_lshl_b32 s96, s15, 7
	v_lshl_add_u64 v[6:7], v[6:7], 0, s[96:97]
	v_lshlrev_b32_e32 v64, 1, v48
	v_lshl_add_u64 v[6:7], v[6:7], 0, v[64:65]
	s_mov_b32 s11, 0xae00000
	v_lshl_add_u64 v[0:1], v[8:9], 0, v[0:1]
	v_add_co_u32_e32 v6, vcc, s11, v6
	s_nop 1
	v_addc_co_u32_e32 v7, vcc, 0, v7, vcc
	global_load_dwordx4 v[44:47], v[0:1], off
	global_load_dwordx2 v[72:73], v[6:7], off offset:2560
	v_add_u32_e32 v0, 0x200, v50
	v_ashrrev_i32_e32 v0, 4, v0
	v_add_u32_e32 v66, s10, v0
	v_ashrrev_i32_e32 v67, 31, v66
	v_lshlrev_b64 v[0:1], 10, v[66:67]
	v_lshl_add_u64 v[6:7], v[2:3], 0, v[0:1]
	v_lshl_add_u64 v[12:13], v[4:5], 0, v[0:1]
	global_load_dwordx4 v[24:27], v[6:7], off
	global_load_dwordx4 v[28:31], v[12:13], off
	v_mad_i64_i32 v[6:7], s[6:7], v66, s93, v[10:11]
	v_lshl_add_u64 v[6:7], v[6:7], 0, s[96:97]
	v_lshl_add_u64 v[6:7], v[6:7], 0, v[64:65]
	v_lshl_add_u64 v[0:1], v[8:9], 0, v[0:1]
	v_add_co_u32_e32 v6, vcc, s11, v6
	s_nop 1
	v_addc_co_u32_e32 v7, vcc, 0, v7, vcc
	global_load_dwordx4 v[32:35], v[0:1], off
	global_load_dwordx2 v[68:69], v[6:7], off offset:2560
	v_add_u32_e32 v0, 0x400, v50
	v_ashrrev_i32_e32 v0, 4, v0
	v_add_u32_e32 v60, s10, v0
	v_ashrrev_i32_e32 v61, 31, v60
	v_lshlrev_b64 v[0:1], 10, v[60:61]
	v_lshl_add_u64 v[6:7], v[2:3], 0, v[0:1]
	v_lshl_add_u64 v[16:17], v[4:5], 0, v[0:1]
	global_load_dwordx4 v[12:15], v[6:7], off
	s_nop 0
	global_load_dwordx4 v[16:19], v[16:17], off
	v_mad_i64_i32 v[6:7], s[6:7], v60, s93, v[10:11]
	v_lshl_add_u64 v[6:7], v[6:7], 0, s[96:97]
	v_lshl_add_u64 v[6:7], v[6:7], 0, v[64:65]
	v_lshl_add_u64 v[0:1], v[8:9], 0, v[0:1]
	v_add_co_u32_e32 v6, vcc, s11, v6
	s_nop 1
	v_addc_co_u32_e32 v7, vcc, 0, v7, vcc
	global_load_dwordx4 v[20:23], v[0:1], off
	global_load_dwordx2 v[62:63], v[6:7], off offset:2560
	v_add_u32_e32 v0, 0x600, v50
	v_ashrrev_i32_e32 v0, 4, v0
	v_add_u32_e32 v56, s10, v0
	v_mad_i64_i32 v[10:11], s[6:7], v56, s93, v[10:11]
	v_ashrrev_i32_e32 v57, 31, v56
	v_lshl_add_u64 v[10:11], v[10:11], 0, s[96:97]
	v_lshlrev_b64 v[52:53], 10, v[56:57]
	v_lshl_add_u64 v[10:11], v[10:11], 0, v[64:65]
	v_lshl_add_u64 v[0:1], v[2:3], 0, v[52:53]
	v_lshl_add_u64 v[4:5], v[4:5], 0, v[52:53]
	v_lshl_add_u64 v[8:9], v[8:9], 0, v[52:53]
	v_add_co_u32_e32 v52, vcc, 0xae00000, v10
	global_load_dwordx4 v[0:3], v[0:1], off
	s_nop 0
	global_load_dwordx4 v[4:7], v[4:5], off
	v_addc_co_u32_e32 v53, vcc, 0, v11, vcc
	global_load_dwordx4 v[8:11], v[8:9], off
	s_nop 0
	global_load_dwordx2 v[58:59], v[52:53], off offset:2560
	s_movk_i32 s6, 0x80
	v_cmp_gt_i32_e32 vcc, s6, v50
	s_and_saveexec_b64 s[10:11], vcc
	s_cbranch_execz .LBB0_1034
	s_add_i32 s16, s16, s15
	s_lshl_b32 s6, s16, 10
	s_add_i32 s96, s6, 0x10000
	s_lshl_b64 s[6:7], s[96:97], 3
	s_add_u32 s6, s8, s6
	s_addc_u32 s7, s9, s7
	s_lshl_b32 s14, s14, 3
	s_lshl_b32 s15, s45, 1
	v_ashrrev_i32_e32 v52, 6, v50
	s_add_i32 s15, s15, s14
	v_add_u32_e32 v54, s15, v52
	s_load_dwordx2 s[14:15], s[0:1], 0x20
	v_and_b32_e32 v49, 63, v50
	v_ashrrev_i32_e32 v55, 31, v54
	v_or_b32_e32 v51, s12, v49
	v_lshlrev_b64 v[54:55], 10, v[54:55]
	s_waitcnt lgkmcnt(0)
	v_lshl_add_u64 v[54:55], s[14:15], 0, v[54:55]
	v_lshlrev_b32_e32 v74, 2, v51
	v_mov_b32_e32 v75, v65
	v_lshl_add_u64 v[54:55], v[54:55], 0, v[74:75]
	global_load_dword v51, v[54:55], off
	v_lshlrev_b32_e32 v54, 3, v49
	v_mov_b32_e32 v55, v65
	v_ashrrev_i32_e32 v53, 31, v52
	v_lshl_add_u64 v[54:55], s[6:7], 0, v[54:55]
	v_lshlrev_b64 v[52:53], 9, v[52:53]
	v_lshl_add_u64 v[52:53], v[54:55], 0, v[52:53]
	s_mov_b64 s[6:7], 0x13800000
	v_lshl_add_u64 v[54:55], v[52:53], 0, s[6:7]
	s_mov_b32 s6, 0x13801000
	v_add_co_u32_e32 v52, vcc, s6, v52
	s_nop 1
	v_addc_co_u32_e32 v53, vcc, 0, v53, vcc
	global_load_dwordx2 v[74:75], v[52:53], off offset:-4096
	global_load_dwordx2 v[76:77], v[54:55], off offset:1024
	global_load_dwordx2 v[78:79], v[54:55], off offset:2048
	s_nop 0
	global_load_dwordx2 v[54:55], v[54:55], off offset:3072
	s_nop 0
	global_load_dwordx2 v[80:81], v[52:53], off
	global_load_dwordx2 v[82:83], v[52:53], off offset:1024
	global_load_dwordx2 v[84:85], v[52:53], off offset:2048
	s_nop 0
	global_load_dwordx2 v[52:53], v[52:53], off offset:3072
	v_cmp_lt_u32_e32 vcc, 63, v50
	s_waitcnt vmcnt(0)
	s_nop 0
	v_cndmask_b32_e32 v50, v75, v53, vcc
	v_cndmask_b32_e32 v52, v74, v52, vcc
	v_fmac_f32_e32 v50, v51, v52
	v_cndmask_b32_e64 v52, 1, 6, vcc
	v_cmp_eq_u32_e64 s[6:7], s13, v52
	v_cndmask_b32_e32 v52, v77, v85, vcc
	v_cndmask_b32_e32 v53, v76, v84, vcc
	v_fmac_f32_e32 v52, v53, v50
	v_cndmask_b32_e64 v50, v51, v50, s[6:7]
	v_cndmask_b32_e64 v51, 2, 5, vcc
	v_cmp_eq_u32_e64 s[6:7], s13, v51
	v_cndmask_b32_e32 v51, v79, v83, vcc
	v_cndmask_b32_e32 v53, v78, v82, vcc
	v_cndmask_b32_e64 v50, v50, v52, s[6:7]
	v_fmac_f32_e32 v51, v53, v52
	v_cndmask_b32_e64 v52, 3, 4, vcc
	v_cmp_eq_u32_e64 s[6:7], s13, v52
	v_cndmask_b32_e32 v52, v55, v81, vcc
	v_cndmask_b32_e32 v53, v54, v80, vcc
	v_cndmask_b32_e64 v50, v50, v51, s[6:7]
	v_fmac_f32_e32 v52, v53, v51
	v_cndmask_b32_e64 v51, 4, 3, vcc
	v_cmp_eq_u32_e64 s[6:7], s13, v51
	v_cndmask_b32_e32 v51, v81, v55, vcc
	v_cndmask_b32_e32 v53, v80, v54, vcc
	v_cndmask_b32_e64 v50, v50, v52, s[6:7]
	v_fmac_f32_e32 v51, v53, v52
	v_cndmask_b32_e64 v52, 5, 2, vcc
	v_cmp_eq_u32_e64 s[6:7], s13, v52
	v_cndmask_b32_e32 v52, v83, v79, vcc
	v_cndmask_b32_e32 v53, v82, v78, vcc
	v_cndmask_b32_e64 v50, v50, v51, s[6:7]
	v_fmac_f32_e32 v52, v53, v51
	v_cndmask_b32_e64 v51, 6, 1, vcc
	v_cmp_eq_u32_e64 s[6:7], s13, v51
	v_cndmask_b32_e32 v51, v85, v77, vcc
	v_cndmask_b32_e32 v53, v84, v76, vcc
	v_cndmask_b32_e64 v50, v50, v52, s[6:7]
	v_fmac_f32_e32 v51, v53, v52
	v_cndmask_b32_e64 v52, 7, 0, vcc
	v_cmp_eq_u32_e64 s[6:7], s13, v52
	s_nop 1
	v_cndmask_b32_e64 v50, v50, v51, s[6:7]
	s_add_i32 s6, 0, 0x100
	v_mov_b32_e32 v51, s6
	v_cndmask_b32_e32 v51, 0, v51, vcc
	v_lshl_add_u32 v49, v49, 2, v51
	ds_write_b32 v49, v50
